# v7 + decode page-table entries loaded once per task (no per-iteration vmcnt(0) drain)
# speedup vs baseline: 1.0282x; 1.0029x over previous
.LBB0_1241:
	s_or_b64 exec, exec, s[10:11]
	s_lshl_b32 s0, s13, 2
	s_and_b32 s0, s0, -16
	s_ashr_i32 s1, s0, 31
	s_lshl_b32 s14, s43, 7
	s_and_b32 s15, s42, 7
	s_lshl_b64 s[0:1], s[0:1], 2
	s_add_u32 s0, s60, s0
	s_addc_u32 s1, s61, s1
	s_lshl_b32 s10, s15, 3
	s_load_dwordx2 s[98:99], s[0:1], s10
	v_mov_b32_e32 v2, s10
	global_load_dword v4, v2, s[0:1]
	v_lshlrev_b32_e32 v5, 13, v139
	v_lshl_or_b32 v6, v123, 4, v5
	s_lshl_b32 s13, s14, 2
	v_lshlrev_b32_e32 v2, 5, v139
	v_mov_b32_e32 v7, v3
	v_lshl_add_u32 v2, v123, 11, v2
	s_lshl_b32 s10, s43, 9
	v_lshlrev_b32_e32 v124, 2, v139
	v_lshl_add_u64 v[128:129], s[56:57], 0, v[2:3]
	s_lshl_b32 s22, s15, 8
	s_add_i32 s43, s10, 0
	v_lshl_add_u64 v[130:131], s[58:59], 0, v[6:7]
	v_sub_u32_e32 v141, v125, v124
	s_add_i32 s43, s43, 0x26a00
	s_waitcnt vmcnt(4)
	v_subrev_u32_e32 v142, s22, v141
	s_mov_b32 s68, 0
	v_mov_b32_e32 v138, 0
	v_mov_b32_e32 v140, 0xf149f2ca
	s_mov_b32 s69, 16
	s_waitcnt vmcnt(0) lgkmcnt(0)
	v_ashrrev_i32_e32 v5, 31, v4
	v_lshlrev_b64 v[4:5], 18, v[4:5]
	v_or_b32_e32 v4, s13, v4
	v_lshl_add_u64 v[8:9], s[56:57], 0, v[4:5]
	v_lshl_add_u64 v[4:5], s[58:59], 0, v[4:5]
	v_lshl_add_u64 v[8:9], v[8:9], 0, v[2:3]
	v_lshl_add_u64 v[4:5], v[4:5], 0, v[6:7]
	v_lshl_add_u64 v[10:11], v[4:5], 0, s[38:39]
	global_load_dwordx4 v[52:55], v[8:9], off offset:16 nt
	global_load_dwordx4 v[56:59], v[8:9], off nt
	global_load_dwordx4 v[60:63], v[8:9], off offset:144 nt
	global_load_dwordx4 v[64:67], v[8:9], off offset:128 nt
	global_load_dwordx4 v[68:71], v[8:9], off offset:272 nt
	global_load_dwordx4 v[72:75], v[8:9], off offset:256 nt
	global_load_dwordx4 v[76:79], v[8:9], off offset:400 nt
	global_load_dwordx4 v[80:83], v[8:9], off offset:384 nt
	global_load_dwordx4 v[84:87], v[4:5], off nt
	global_load_dwordx4 v[88:91], v[4:5], off offset:256 nt
	global_load_dwordx4 v[92:95], v[4:5], off offset:2048 nt
	global_load_dwordx4 v[96:99], v[4:5], off offset:2304 nt
	global_load_dwordx4 v[100:103], v[10:11], off nt
	global_load_dwordx4 v[104:107], v[10:11], off offset:256 nt
	global_load_dwordx4 v[108:111], v[10:11], off offset:2048 nt
	global_load_dwordx4 v[112:115], v[10:11], off offset:2304 nt
	v_mov_b32_e32 v4, v3
	v_mov_b32_e32 v5, v3
	v_mov_b32_e32 v2, v3
	v_mov_b64_e32 v[22:23], v[4:5]
	v_mov_b64_e32 v[30:31], v[4:5]
	v_mov_b64_e32 v[34:35], v[4:5]
	v_mov_b64_e32 v[26:27], v[4:5]
	v_mov_b64_e32 v[10:11], v[4:5]
	v_mov_b64_e32 v[14:15], v[4:5]
	v_mov_b64_e32 v[18:19], v[4:5]
	v_mov_b64_e32 v[20:21], v[2:3]
	v_mov_b64_e32 v[28:29], v[2:3]
	v_mov_b64_e32 v[32:33], v[2:3]
	v_mov_b64_e32 v[24:25], v[2:3]
	v_mov_b64_e32 v[8:9], v[2:3]
	v_mov_b64_e32 v[12:13], v[2:3]
	v_mov_b64_e32 v[16:17], v[2:3]
	v_mov_b64_e32 v[6:7], v[4:5]
	v_mov_b64_e32 v[4:5], v[2:3]
	s_branch .LBB0_1243

.LBB0_1243:
	s_add_i32 s70, s22, s69
	s_cmpk_eq_i32 s68, 0xff10
	s_cbranch_scc1 .LBB0_1245
	s_bitcmp1_b32 s70, 7
	s_cselect_b32 s10, s99, s98
	v_mov_b32_e32 v116, s10
	s_and_b32 s10, s69, 0x70
	v_ashrrev_i32_e32 v117, 31, v116
	v_lshlrev_b64 v[116:117], 7, v[116:117]
	v_or_b32_e32 v116, s10, v116
	s_add_i32 s10, s70, -16
	s_cbranch_execz .LBB0_1246
	s_branch .LBB0_1247

.LBB0_1246:
	s_bitcmp1_b32 s10, 7
	s_cselect_b32 s11, s99, s98
	v_mov_b32_e32 v116, s11
	v_ashrrev_i32_e32 v117, 31, v116
	v_lshlrev_b64 v[116:117], 7, v[116:117]
	v_or_b32_e32 v116, 0x70, v116

	.amdhsa_kernel _Z6mk_fwd4Args
		.amdhsa_group_segment_fixed_size 0
		.amdhsa_private_segment_fixed_size 0
		.amdhsa_kernarg_size 528
		.amdhsa_user_sgpr_count 2
		.amdhsa_user_sgpr_dispatch_ptr 0
		.amdhsa_user_sgpr_queue_ptr 0
		.amdhsa_user_sgpr_kernarg_segment_ptr 1
		.amdhsa_user_sgpr_dispatch_id 0
		.amdhsa_user_sgpr_kernarg_preload_length 0
		.amdhsa_user_sgpr_kernarg_preload_offset 0
		.amdhsa_user_sgpr_private_segment_size 0
		.amdhsa_uses_dynamic_stack 0
		.amdhsa_enable_private_segment 0
		.amdhsa_system_sgpr_workgroup_id_x 1
		.amdhsa_system_sgpr_workgroup_id_y 0
		.amdhsa_system_sgpr_workgroup_id_z 0
		.amdhsa_system_sgpr_workgroup_info 0
		.amdhsa_system_vgpr_workitem_id 0
		.amdhsa_next_free_vgpr 256
		.amdhsa_next_free_sgpr 102
		.amdhsa_accum_offset 256
		.amdhsa_reserve_vcc 1
		.amdhsa_float_round_mode_32 0
		.amdhsa_float_round_mode_16_64 0
		.amdhsa_float_denorm_mode_32 3
		.amdhsa_float_denorm_mode_16_64 3
		.amdhsa_dx10_clamp 1
		.amdhsa_ieee_mode 1
		.amdhsa_fp16_overflow 0
		.amdhsa_tg_split 0
		.amdhsa_exception_fp_ieee_invalid_op 0
		.amdhsa_exception_fp_denorm_src 0
		.amdhsa_exception_fp_ieee_div_zero 0
		.amdhsa_exception_fp_ieee_overflow 0
		.amdhsa_exception_fp_ieee_underflow 0
		.amdhsa_exception_fp_ieee_inexact 0
		.amdhsa_exception_int_div_zero 0
	.end_amdhsa_kernel

amdhsa.kernels:
  - .agpr_count:     0
    .args:
      - .offset:         0
        .size:           272
        .value_kind:     by_value
      - .offset:         272
        .size:           4
        .value_kind:     hidden_block_count_x
      - .offset:         276
        .size:           4
        .value_kind:     hidden_block_count_y
      - .offset:         280
        .size:           4
        .value_kind:     hidden_block_count_z
      - .offset:         284
        .size:           2
        .value_kind:     hidden_group_size_x
      - .offset:         286
        .size:           2
        .value_kind:     hidden_group_size_y
      - .offset:         288
        .size:           2
        .value_kind:     hidden_group_size_z
      - .offset:         290
        .size:           2
        .value_kind:     hidden_remainder_x
      - .offset:         292
        .size:           2
        .value_kind:     hidden_remainder_y
      - .offset:         294
        .size:           2
        .value_kind:     hidden_remainder_z
      - .offset:         312
        .size:           8
        .value_kind:     hidden_global_offset_x
      - .offset:         320
        .size:           8
        .value_kind:     hidden_global_offset_y
      - .offset:         328
        .size:           8
        .value_kind:     hidden_global_offset_z
      - .offset:         336
        .size:           2
        .value_kind:     hidden_grid_dims
      - .offset:         392
        .size:           4
        .value_kind:     hidden_dynamic_lds_size
    .group_segment_fixed_size: 0
    .kernarg_segment_align: 8
    .kernarg_segment_size: 528
    .language:       OpenCL C
    .language_version:
      - 2
      - 0
    .max_flat_workgroup_size: 512
    .name:           _Z6mk_fwd4Args
    .private_segment_fixed_size: 0
    .sgpr_count:     108
    .sgpr_spill_count: 58
    .symbol:         _Z6mk_fwd4Args.kd
    .uniform_work_group_size: 1
    .uses_dynamic_stack: false
    .vgpr_count:     256
    .vgpr_spill_count: 0
    .wavefront_size: 64
